# relu2 epilogue: rstd loads hoisted, no per-group drains (unpaced stores)
# speedup vs baseline: 1.0031x; 1.0031x over previous
.LBB0_564:
	s_mul_i32 s51, s45, 0x6000
	s_add_i32 s52, s51, 0xffffa000
	s_cmp_lg_u32 s45, 0
	s_cselect_b32 s52, s52, 0xc000
	v_add_u32_e32 v146, s52, v138
	v_lshl_add_u64 v[142:143], v[134:135], 0, s[48:49]
	v_readfirstlane_b32 s52, v146
	v_add_u32_e32 v147, 0x1000, v146
	v_lshl_add_u64 v[144:145], v[142:143], 0, s[22:23]
	s_mov_b32 m0, s52
	v_readfirstlane_b32 s52, v147
	v_add_u32_e32 v147, 0x2000, v146
	s_waitcnt vmcnt(6)
	s_barrier
	global_load_lds_dwordx4 v[144:145], off
	v_lshl_add_u64 v[144:145], v[142:143], 0, s[24:25]
	s_mov_b32 m0, s52
	v_readfirstlane_b32 s52, v147
	global_load_lds_dwordx4 v[144:145], off
	v_lshl_add_u64 v[144:145], v[142:143], 0, s[26:27]
	s_mov_b32 m0, s52
	v_lshl_add_u64 v[142:143], v[142:143], 0, s[28:29]
	global_load_lds_dwordx4 v[144:145], off
	v_add_u32_e32 v144, 0x3000, v146
	v_add_u32_e32 v147, 0x4000, v146
	v_readfirstlane_b32 s52, v144
	s_mov_b32 m0, s52
	v_readfirstlane_b32 s52, v147
	global_load_lds_dwordx4 v[142:143], off
	v_lshl_add_u64 v[142:143], v[132:133], 0, s[48:49]
	v_lshl_add_u64 v[144:145], v[142:143], 0, s[30:31]
	s_mov_b32 m0, s52
	v_lshl_add_u64 v[142:143], v[142:143], 0, s[34:35]
	global_load_lds_dwordx4 v[144:145], off
	v_add_u32_e32 v144, 0x5000, v146
	s_add_i32 s51, s51, 0
	v_readfirstlane_b32 s52, v144
	s_mov_b32 m0, s52
	v_add3_u32 v154, s51, v139, v141
	global_load_lds_dwordx4 v[142:143], off
	v_add3_u32 v174, s51, v140, v141
	ds_read_b128 v[142:145], v154 offset:16384
	ds_read_b128 v[146:149], v154 offset:17408
	ds_read_b128 v[150:153], v154 offset:18432
	ds_read_b128 v[154:157], v154 offset:19456
	ds_read_b128 v[158:161], v174
	ds_read_b128 v[162:165], v174 offset:1024
	ds_read_b128 v[166:169], v174 offset:2048
	ds_read_b128 v[170:173], v174 offset:3072
	s_setprio 1
	s_waitcnt lgkmcnt(0)
	v_mfma_f32_16x16x32_bf16 v[126:129], v[142:145], v[158:161], v[126:129]
	v_mfma_f32_16x16x32_bf16 v[122:125], v[146:149], v[158:161], v[122:125]
	v_mfma_f32_16x16x32_bf16 v[118:121], v[150:153], v[158:161], v[118:121]
	v_mfma_f32_16x16x32_bf16 v[114:117], v[154:157], v[158:161], v[114:117]
	v_mfma_f32_16x16x32_bf16 v[110:113], v[142:145], v[162:165], v[110:113]
	v_mfma_f32_16x16x32_bf16 v[106:109], v[146:149], v[162:165], v[106:109]
	v_mfma_f32_16x16x32_bf16 v[102:105], v[150:153], v[162:165], v[102:105]
	v_mfma_f32_16x16x32_bf16 v[98:101], v[154:157], v[162:165], v[98:101]
	v_mfma_f32_16x16x32_bf16 v[94:97], v[142:145], v[166:169], v[94:97]
	v_mfma_f32_16x16x32_bf16 v[90:93], v[146:149], v[166:169], v[90:93]
	v_mfma_f32_16x16x32_bf16 v[86:89], v[150:153], v[166:169], v[86:89]
	v_mfma_f32_16x16x32_bf16 v[82:85], v[154:157], v[166:169], v[82:85]
	v_mfma_f32_16x16x32_bf16 v[78:81], v[142:145], v[170:173], v[78:81]
	v_mfma_f32_16x16x32_bf16 v[74:77], v[146:149], v[170:173], v[74:77]
	v_mfma_f32_16x16x32_bf16 v[70:73], v[150:153], v[170:173], v[70:73]
	v_mfma_f32_16x16x32_bf16 v[66:69], v[154:157], v[170:173], v[66:69]
	s_setprio 0
	ds_read_b128 v[158:161], v174 offset:4096
	ds_read_b128 v[162:165], v174 offset:5120
	ds_read_b128 v[166:169], v174 offset:6144
	ds_read_b128 v[170:173], v174 offset:7168
	s_setprio 1
	s_waitcnt lgkmcnt(0)
	v_mfma_f32_16x16x32_bf16 v[62:65], v[142:145], v[158:161], v[62:65]
	v_mfma_f32_16x16x32_bf16 v[58:61], v[146:149], v[158:161], v[58:61]
	v_mfma_f32_16x16x32_bf16 v[54:57], v[150:153], v[158:161], v[54:57]
	v_mfma_f32_16x16x32_bf16 v[50:53], v[154:157], v[158:161], v[50:53]
	v_mfma_f32_16x16x32_bf16 v[46:49], v[142:145], v[162:165], v[46:49]
	v_mfma_f32_16x16x32_bf16 v[42:45], v[146:149], v[162:165], v[42:45]
	v_mfma_f32_16x16x32_bf16 v[38:41], v[150:153], v[162:165], v[38:41]
	v_mfma_f32_16x16x32_bf16 v[34:37], v[154:157], v[162:165], v[34:37]
	v_mfma_f32_16x16x32_bf16 v[30:33], v[142:145], v[166:169], v[30:33]
	v_mfma_f32_16x16x32_bf16 v[26:29], v[146:149], v[166:169], v[26:29]
	v_mfma_f32_16x16x32_bf16 v[22:25], v[150:153], v[166:169], v[22:25]
	v_mfma_f32_16x16x32_bf16 v[18:21], v[154:157], v[166:169], v[18:21]
	v_mfma_f32_16x16x32_bf16 v[14:17], v[142:145], v[170:173], v[14:17]
	v_mfma_f32_16x16x32_bf16 v[10:13], v[146:149], v[170:173], v[10:13]
	v_mfma_f32_16x16x32_bf16 v[6:9], v[150:153], v[170:173], v[6:9]
	v_mfma_f32_16x16x32_bf16 v[2:5], v[154:157], v[170:173], v[2:5]
	s_setprio 0
	s_add_i32 s51, s45, 1
	s_cmp_lg_u32 s45, 2
	s_cselect_b32 s45, s51, 0
	s_add_u32 s48, s48, 64
	s_addc_u32 s49, s49, 0
	s_cmpk_eq_i32 s48, 0x780
	s_cbranch_scc0 .LBB0_564
	v_add3_u32 v166, 0, v139, v141
	v_add3_u32 v167, 0, v140, v141
	s_waitcnt vmcnt(6)
	s_barrier
	ds_read_b128 v[132:135], v166 offset:16384
	ds_read_b128 v[142:145], v166 offset:17408
	ds_read_b128 v[146:149], v166 offset:18432
	ds_read_b128 v[150:153], v166 offset:19456
	ds_read_b128 v[138:141], v167
	ds_read_b128 v[154:157], v167 offset:1024
	ds_read_b128 v[158:161], v167 offset:2048
	ds_read_b128 v[162:165], v167 offset:3072
	s_setprio 1
	s_waitcnt lgkmcnt(0)
	v_mfma_f32_16x16x32_bf16 v[126:129], v[132:135], v[138:141], v[126:129]
	v_mfma_f32_16x16x32_bf16 v[122:125], v[142:145], v[138:141], v[122:125]
	v_mfma_f32_16x16x32_bf16 v[118:121], v[146:149], v[138:141], v[118:121]
	v_mfma_f32_16x16x32_bf16 v[114:117], v[150:153], v[138:141], v[114:117]
	v_mfma_f32_16x16x32_bf16 v[110:113], v[132:135], v[154:157], v[110:113]
	v_mfma_f32_16x16x32_bf16 v[106:109], v[142:145], v[154:157], v[106:109]
	v_mfma_f32_16x16x32_bf16 v[102:105], v[146:149], v[154:157], v[102:105]
	v_mfma_f32_16x16x32_bf16 v[98:101], v[150:153], v[154:157], v[98:101]
	v_mfma_f32_16x16x32_bf16 v[94:97], v[132:135], v[158:161], v[94:97]
	v_mfma_f32_16x16x32_bf16 v[90:93], v[142:145], v[158:161], v[90:93]
	v_mfma_f32_16x16x32_bf16 v[86:89], v[146:149], v[158:161], v[86:89]
	v_mfma_f32_16x16x32_bf16 v[82:85], v[150:153], v[158:161], v[82:85]
	v_mfma_f32_16x16x32_bf16 v[78:81], v[132:135], v[162:165], v[78:81]
	v_mfma_f32_16x16x32_bf16 v[74:77], v[142:145], v[162:165], v[74:77]
	v_mfma_f32_16x16x32_bf16 v[70:73], v[146:149], v[162:165], v[70:73]
	v_mfma_f32_16x16x32_bf16 v[66:69], v[150:153], v[162:165], v[66:69]
	s_setprio 0
	ds_read_b128 v[138:141], v167 offset:4096
	ds_read_b128 v[154:157], v167 offset:5120
	ds_read_b128 v[158:161], v167 offset:6144
	ds_read_b128 v[162:165], v167 offset:7168
	s_setprio 1
	s_waitcnt lgkmcnt(0)
	v_mfma_f32_16x16x32_bf16 v[62:65], v[132:135], v[138:141], v[62:65]
	v_mfma_f32_16x16x32_bf16 v[58:61], v[142:145], v[138:141], v[58:61]
	v_mfma_f32_16x16x32_bf16 v[54:57], v[146:149], v[138:141], v[54:57]
	v_mfma_f32_16x16x32_bf16 v[50:53], v[150:153], v[138:141], v[50:53]
	v_mfma_f32_16x16x32_bf16 v[46:49], v[132:135], v[154:157], v[46:49]
	v_mfma_f32_16x16x32_bf16 v[42:45], v[142:145], v[154:157], v[42:45]
	v_mfma_f32_16x16x32_bf16 v[38:41], v[146:149], v[154:157], v[38:41]
	v_mfma_f32_16x16x32_bf16 v[34:37], v[150:153], v[154:157], v[34:37]
	v_mfma_f32_16x16x32_bf16 v[30:33], v[132:135], v[158:161], v[30:33]
	v_mfma_f32_16x16x32_bf16 v[26:29], v[142:145], v[158:161], v[26:29]
	v_mfma_f32_16x16x32_bf16 v[22:25], v[146:149], v[158:161], v[22:25]
	v_mfma_f32_16x16x32_bf16 v[18:21], v[150:153], v[158:161], v[18:21]
	v_mfma_f32_16x16x32_bf16 v[14:17], v[132:135], v[162:165], v[14:17]
	v_mfma_f32_16x16x32_bf16 v[10:13], v[142:145], v[162:165], v[10:13]
	v_mfma_f32_16x16x32_bf16 v[6:9], v[146:149], v[162:165], v[6:9]
	v_mfma_f32_16x16x32_bf16 v[2:5], v[150:153], v[162:165], v[2:5]
	s_setprio 0
	s_waitcnt vmcnt(0)
	s_barrier
	ds_read_b128 v[132:135], v166 offset:40960
	ds_read_b128 v[138:141], v166 offset:41984
	ds_read_b128 v[142:145], v166 offset:43008
	ds_read_b128 v[146:149], v166 offset:44032
	ds_read_b128 v[150:153], v167 offset:24576
	ds_read_b128 v[154:157], v167 offset:25600
	ds_read_b128 v[158:161], v167 offset:26624
	ds_read_b128 v[162:165], v167 offset:27648
	s_lshl_b64 s[46:47], s[46:47], 8
	v_lshl_add_u64 v[184:185], s[46:47], 0, v[130:131]
	v_lshl_add_u64 v[184:185], v[184:185], 2, s[8:9]
	global_load_dword v176, v[184:185], off
	global_load_dword v177, v[184:185], off offset:64
	global_load_dword v178, v[184:185], off offset:128
	global_load_dword v179, v[184:185], off offset:192
	global_load_dword v180, v[184:185], off offset:256
	global_load_dword v181, v[184:185], off offset:320
	global_load_dword v182, v[184:185], off offset:384
	global_load_dword v183, v[184:185], off offset:448
	s_setprio 1
	s_waitcnt lgkmcnt(0)
	v_mfma_f32_16x16x32_bf16 v[126:129], v[132:135], v[150:153], v[126:129]
	v_mfma_f32_16x16x32_bf16 v[122:125], v[138:141], v[150:153], v[122:125]
	v_mfma_f32_16x16x32_bf16 v[118:121], v[142:145], v[150:153], v[118:121]
	v_mfma_f32_16x16x32_bf16 v[114:117], v[146:149], v[150:153], v[114:117]
	v_mfma_f32_16x16x32_bf16 v[110:113], v[132:135], v[154:157], v[110:113]
	v_mfma_f32_16x16x32_bf16 v[150:153], v[138:141], v[154:157], v[106:109]
	v_mfma_f32_16x16x32_bf16 v[102:105], v[142:145], v[154:157], v[102:105]
	v_mfma_f32_16x16x32_bf16 v[98:101], v[146:149], v[154:157], v[98:101]
	v_mfma_f32_16x16x32_bf16 v[94:97], v[132:135], v[158:161], v[94:97]
	v_mfma_f32_16x16x32_bf16 v[90:93], v[138:141], v[158:161], v[90:93]
	v_mfma_f32_16x16x32_bf16 v[86:89], v[142:145], v[158:161], v[86:89]
	v_mfma_f32_16x16x32_bf16 v[82:85], v[146:149], v[158:161], v[82:85]
	v_mfma_f32_16x16x32_bf16 v[78:81], v[132:135], v[162:165], v[78:81]
	v_mfma_f32_16x16x32_bf16 v[74:77], v[138:141], v[162:165], v[74:77]
	v_mfma_f32_16x16x32_bf16 v[70:73], v[142:145], v[162:165], v[70:73]
	v_mfma_f32_16x16x32_bf16 v[66:69], v[146:149], v[162:165], v[66:69]
	s_setprio 0
	ds_read_b128 v[106:109], v167 offset:28672
	ds_read_b128 v[154:157], v167 offset:29696
	ds_read_b128 v[158:161], v167 offset:30720
	ds_read_b128 v[162:165], v167 offset:31744
	s_setprio 1
	s_waitcnt lgkmcnt(0)
	v_mfma_f32_16x16x32_bf16 v[62:65], v[132:135], v[106:109], v[62:65]
	v_mfma_f32_16x16x32_bf16 v[58:61], v[138:141], v[106:109], v[58:61]
	v_mfma_f32_16x16x32_bf16 v[54:57], v[142:145], v[106:109], v[54:57]
	v_mfma_f32_16x16x32_bf16 v[50:53], v[146:149], v[106:109], v[50:53]
	v_mfma_f32_16x16x32_bf16 v[46:49], v[132:135], v[154:157], v[46:49]
	v_mfma_f32_16x16x32_bf16 v[42:45], v[138:141], v[154:157], v[42:45]
	v_mfma_f32_16x16x32_bf16 v[38:41], v[142:145], v[154:157], v[38:41]
	v_mfma_f32_16x16x32_bf16 v[34:37], v[146:149], v[154:157], v[34:37]
	v_mfma_f32_16x16x32_bf16 v[30:33], v[132:135], v[158:161], v[30:33]
	v_mfma_f32_16x16x32_bf16 v[26:29], v[138:141], v[158:161], v[26:29]
	v_mfma_f32_16x16x32_bf16 v[22:25], v[142:145], v[158:161], v[22:25]
	v_mfma_f32_16x16x32_bf16 v[18:21], v[146:149], v[158:161], v[18:21]
	v_mfma_f32_16x16x32_bf16 v[14:17], v[132:135], v[162:165], v[14:17]
	v_mfma_f32_16x16x32_bf16 v[10:13], v[138:141], v[162:165], v[10:13]
	v_mfma_f32_16x16x32_bf16 v[6:9], v[142:145], v[162:165], v[6:9]
	v_mfma_f32_16x16x32_bf16 v[2:5], v[146:149], v[162:165], v[2:5]
	s_setprio 0
	v_lshl_add_u64 v[106:107], s[46:47], 0, v[130:131]
	v_lshl_add_u64 v[108:109], v[106:107], 2, s[8:9]
	s_waitcnt vmcnt(0)
	s_barrier
	v_max_f32_e32 v109, v126, v126
	v_max_f32_e32 v126, v127, v127
	v_max_f32_e32 v127, v128, v128
	v_max_f32_e32 v128, v129, v129
	v_max_f32_e32 v122, v122, v122
	v_max_f32_e32 v124, v124, v124
	v_max_f32_e32 v129, v118, v118
	v_max_f32_e32 v139, v115, v115
	v_max_f32_e32 v133, v120, v120
	v_max_f32_e32 v120, 0, v122
	v_max_f32_e32 v122, 0, v124
	v_max_f32_e32 v124, 0, v129
	v_max_f32_e32 v129, 0, v139
	v_max_f32_e32 v123, v123, v123
	v_max_f32_e32 v125, v125, v125
	v_max_f32_e32 v132, v119, v119
	v_max_f32_e32 v140, v116, v116
	v_max_f32_e32 v134, v121, v121
	v_max_f32_e32 v121, 0, v123
	v_max_f32_e32 v123, 0, v125
	v_max_f32_e32 v125, 0, v132
	v_max_f32_e32 v132, 0, v140
	v_max_f32_e32 v141, v117, v117
	v_max_f32_e32 v117, 0, v126
	v_max_f32_e32 v126, 0, v133
	v_max_f32_e32 v133, 0, v141
	v_lshl_or_b32 v108, s44, 7, v136
	v_max_f32_e32 v135, v114, v114
	v_max_f32_e32 v116, 0, v109
	v_max_f32_e32 v118, 0, v127
	v_max_f32_e32 v119, 0, v128
	v_lshlrev_b64 v[114:115], 13, v[106:107]
	v_ashrrev_i32_e32 v109, 31, v108
	v_max_f32_e32 v127, 0, v134
	v_max_f32_e32 v128, 0, v135
	v_lshl_add_u64 v[114:115], s[6:7], 0, v[114:115]
	v_lshlrev_b64 v[108:109], 1, v[108:109]
	v_or_b32_e32 v134, 16, v106
	v_mov_b32_e32 v135, v107
	v_lshl_add_u64 v[114:115], v[114:115], 0, v[108:109]
	v_max_f32_e32 v110, v110, v110
	v_max_f32_e32 v111, v111, v111
	v_max_f32_e32 v112, v112, v112
	v_max_f32_e32 v113, v113, v113
	v_max_f32_e32 v94, v94, v94
	v_max_f32_e32 v95, v95, v95
	v_max_f32_e32 v96, v96, v96
	v_max_f32_e32 v97, v97, v97
	v_max_f32_e32 v90, v90, v90
	v_max_f32_e32 v91, v91, v91
	v_max_f32_e32 v92, v92, v92
	v_max_f32_e32 v93, v93, v93
	v_max_f32_e32 v78, v78, v78
	v_max_f32_e32 v79, v79, v79
	v_max_f32_e32 v80, v80, v80
	v_max_f32_e32 v81, v81, v81
	v_max_f32_e32 v74, v74, v74
	v_max_f32_e32 v75, v75, v75
	v_max_f32_e32 v76, v76, v76
	v_max_f32_e32 v77, v77, v77
	v_max_f32_e32 v62, v62, v62
	v_max_f32_e32 v63, v63, v63
	v_max_f32_e32 v64, v64, v64
	v_max_f32_e32 v65, v65, v65
	v_max_f32_e32 v58, v58, v58
	v_max_f32_e32 v59, v59, v59
	v_max_f32_e32 v60, v60, v60
	v_max_f32_e32 v61, v61, v61
	v_max_f32_e32 v46, v46, v46
	v_max_f32_e32 v47, v47, v47
	v_max_f32_e32 v48, v48, v48
	v_max_f32_e32 v49, v49, v49
	v_max_f32_e32 v42, v42, v42
	v_max_f32_e32 v43, v43, v43
	v_max_f32_e32 v44, v44, v44
	v_max_f32_e32 v45, v45, v45
	v_max_f32_e32 v28, v28, v28
	v_max_f32_e32 v29, v29, v29
	v_max_f32_e32 v30, v30, v30
	v_fmamk_f32 v138, v176, 0x3a800000, v137
	v_mul_f32_e32 v139, 0x4b800000, v138
	v_cmp_gt_f32_e32 vcc, s43, v138
	v_max_f32_e32 v31, v31, v31
	v_max_f32_e32 v32, v32, v32
	v_cndmask_b32_e32 v138, v138, v139, vcc
	v_rsq_f32_e32 v140, v138
	v_lshl_add_u64 v[138:139], v[134:135], 2, s[8:9]
	v_max_f32_e32 v33, v33, v33
	v_max_f32_e32 v26, v26, v26
	v_mul_f32_e32 v141, 0x45800000, v140
	v_cndmask_b32_e32 v140, v140, v141, vcc
	v_pk_mul_f32 v[116:117], v[116:117], v[140:141] op_sel_hi:[1,0]
	v_pk_mul_f32 v[118:119], v[118:119], v[140:141] op_sel_hi:[1,0]
	v_pk_mul_f32 v[120:121], v[120:121], v[140:141] op_sel_hi:[1,0]
	v_pk_mul_f32 v[122:123], v[122:123], v[140:141] op_sel_hi:[1,0]
	v_pk_mul_f32 v[124:125], v[124:125], v[140:141] op_sel_hi:[1,0]
	v_pk_mul_f32 v[126:127], v[126:127], v[140:141] op_sel_hi:[1,0]
	v_pk_mul_f32 v[128:129], v[128:129], v[140:141] op_sel_hi:[1,0]
	v_pk_mul_f32 v[132:133], v[132:133], v[140:141] op_sel_hi:[1,0]
	v_pk_mul_f32 v[116:117], v[116:117], v[116:117]
	v_pk_mul_f32 v[118:119], v[118:119], v[118:119]
	v_pk_mul_f32 v[120:121], v[120:121], v[120:121]
	v_pk_mul_f32 v[122:123], v[122:123], v[122:123]
	v_pk_mul_f32 v[124:125], v[124:125], v[124:125]
	v_pk_mul_f32 v[126:127], v[126:127], v[126:127]
	v_pk_mul_f32 v[128:129], v[128:129], v[128:129]
	v_pk_mul_f32 v[132:133], v[132:133], v[132:133]
	v_cvt_pk_bf16_f32 v116, v116, v117
	v_cvt_pk_bf16_f32 v117, v118, v119
	v_cvt_pk_bf16_f32 v118, v120, v121
	v_cvt_pk_bf16_f32 v119, v122, v123
	v_cvt_pk_bf16_f32 v120, v124, v125
	v_cvt_pk_bf16_f32 v121, v126, v127
	v_cvt_pk_bf16_f32 v122, v128, v129
	v_cvt_pk_bf16_f32 v123, v132, v133
	global_store_dwordx2 v[114:115], v[116:117], off
	global_store_dwordx2 v[114:115], v[118:119], off offset:32
	global_store_dwordx2 v[114:115], v[120:121], off offset:64
	global_store_dwordx2 v[114:115], v[122:123], off offset:96
	v_max_f32_e32 v114, v150, v150
	v_max_f32_e32 v123, v98, v98
	v_max_f32_e32 v118, v102, v102
	v_max_f32_e32 v102, 0, v114
	v_max_f32_e32 v114, 0, v123
	v_max_f32_e32 v115, v151, v151
	v_max_f32_e32 v124, v99, v99
	v_max_f32_e32 v119, v103, v103
	v_max_f32_e32 v103, 0, v115
	v_max_f32_e32 v115, 0, v124
	v_max_f32_e32 v116, v152, v152
	v_max_f32_e32 v125, v100, v100
	v_max_f32_e32 v120, v104, v104
	v_max_f32_e32 v104, 0, v116
	v_max_f32_e32 v116, 0, v125
	v_max_f32_e32 v117, v153, v153
	v_max_f32_e32 v121, v105, v105
	v_max_f32_e32 v126, v101, v101
	v_max_f32_e32 v98, 0, v110
	v_max_f32_e32 v99, 0, v111
	v_max_f32_e32 v100, 0, v112
	v_max_f32_e32 v101, 0, v113
	v_max_f32_e32 v105, 0, v117
	v_max_f32_e32 v110, 0, v118
	v_max_f32_e32 v111, 0, v119
	v_max_f32_e32 v112, 0, v120
	v_max_f32_e32 v113, 0, v121
	v_max_f32_e32 v117, 0, v126
	v_lshlrev_b64 v[120:121], 13, v[134:135]
	v_lshl_add_u64 v[120:121], s[6:7], 0, v[120:121]
	v_or_b32_e32 v118, 32, v106
	v_mov_b32_e32 v119, v107
	v_lshl_add_u64 v[120:121], v[120:121], 0, v[108:109]
	v_max_f32_e32 v27, v27, v27
	v_max_f32_e32 v10, v10, v10
	v_max_f32_e32 v11, v11, v11
	v_max_f32_e32 v12, v12, v12
	v_max_f32_e32 v14, v14, v14
	v_max_f32_e32 v15, v15, v15
	v_max_f32_e32 v16, v16, v16
	v_max_f32_e32 v17, v17, v17
	v_max_f32_e32 v13, v13, v13
	s_add_i32 s50, s50, s40
	s_cmpk_gt_i32 s50, 0x1fff
	v_fmamk_f32 v122, v177, 0x3a800000, v137
	v_mul_f32_e32 v123, 0x4b800000, v122
	v_cmp_gt_f32_e32 vcc, s43, v122
	s_nop 1
	v_cndmask_b32_e32 v122, v122, v123, vcc
	v_rsq_f32_e32 v124, v122
	v_lshl_add_u64 v[122:123], v[118:119], 2, s[8:9]
	v_mul_f32_e32 v125, 0x45800000, v124
	v_cndmask_b32_e32 v124, v124, v125, vcc
	v_pk_mul_f32 v[98:99], v[98:99], v[124:125] op_sel_hi:[1,0]
	v_pk_mul_f32 v[100:101], v[100:101], v[124:125] op_sel_hi:[1,0]
	v_pk_mul_f32 v[102:103], v[102:103], v[124:125] op_sel_hi:[1,0]
	v_pk_mul_f32 v[104:105], v[104:105], v[124:125] op_sel_hi:[1,0]
	v_pk_mul_f32 v[110:111], v[110:111], v[124:125] op_sel_hi:[1,0]
	v_pk_mul_f32 v[112:113], v[112:113], v[124:125] op_sel_hi:[1,0]
	v_pk_mul_f32 v[114:115], v[114:115], v[124:125] op_sel_hi:[1,0]
	v_pk_mul_f32 v[116:117], v[116:117], v[124:125] op_sel_hi:[1,0]
	v_pk_mul_f32 v[98:99], v[98:99], v[98:99]
	v_pk_mul_f32 v[100:101], v[100:101], v[100:101]
	v_pk_mul_f32 v[102:103], v[102:103], v[102:103]
	v_pk_mul_f32 v[104:105], v[104:105], v[104:105]
	v_pk_mul_f32 v[110:111], v[110:111], v[110:111]
	v_pk_mul_f32 v[112:113], v[112:113], v[112:113]
	v_pk_mul_f32 v[114:115], v[114:115], v[114:115]
	v_pk_mul_f32 v[116:117], v[116:117], v[116:117]
	v_cvt_pk_bf16_f32 v98, v98, v99
	v_cvt_pk_bf16_f32 v99, v100, v101
	v_cvt_pk_bf16_f32 v100, v102, v103
	v_cvt_pk_bf16_f32 v101, v104, v105
	v_cvt_pk_bf16_f32 v102, v110, v111
	v_cvt_pk_bf16_f32 v103, v112, v113
	v_cvt_pk_bf16_f32 v104, v114, v115
	v_cvt_pk_bf16_f32 v105, v116, v117
	global_store_dwordx2 v[120:121], v[98:99], off
	global_store_dwordx2 v[120:121], v[100:101], off offset:32
	global_store_dwordx2 v[120:121], v[102:103], off offset:64
	global_store_dwordx2 v[120:121], v[104:105], off offset:96
	v_max_f32_e32 v103, v82, v82
	v_max_f32_e32 v82, 0, v94
	v_max_f32_e32 v94, 0, v103
	v_max_f32_e32 v104, v83, v83
	v_max_f32_e32 v83, 0, v95
	v_max_f32_e32 v95, 0, v104
	v_max_f32_e32 v105, v84, v84
	v_max_f32_e32 v84, 0, v96
	v_max_f32_e32 v96, 0, v105
	v_max_f32_e32 v98, v86, v86
	v_max_f32_e32 v99, v87, v87
	v_max_f32_e32 v100, v88, v88
	v_max_f32_e32 v101, v89, v89
	v_max_f32_e32 v110, v85, v85
	v_max_f32_e32 v85, 0, v97
	v_max_f32_e32 v86, 0, v90
	v_max_f32_e32 v87, 0, v91
	v_max_f32_e32 v88, 0, v92
	v_max_f32_e32 v89, 0, v93
	v_max_f32_e32 v90, 0, v98
	v_max_f32_e32 v91, 0, v99
	v_max_f32_e32 v92, 0, v100
	v_max_f32_e32 v93, 0, v101
	v_max_f32_e32 v97, 0, v110
	v_lshlrev_b64 v[100:101], 13, v[118:119]
	v_lshl_add_u64 v[100:101], s[6:7], 0, v[100:101]
	v_or_b32_e32 v98, 48, v106
	v_mov_b32_e32 v99, v107
	v_lshl_add_u64 v[100:101], v[100:101], 0, v[108:109]
	v_fmamk_f32 v102, v178, 0x3a800000, v137
	v_mul_f32_e32 v103, 0x4b800000, v102
	v_cmp_gt_f32_e32 vcc, s43, v102
	s_nop 1
	v_cndmask_b32_e32 v102, v102, v103, vcc
	v_rsq_f32_e32 v104, v102
	v_lshl_add_u64 v[102:103], v[98:99], 2, s[8:9]
	v_mul_f32_e32 v105, 0x45800000, v104
	v_cndmask_b32_e32 v104, v104, v105, vcc
	v_pk_mul_f32 v[82:83], v[82:83], v[104:105] op_sel_hi:[1,0]
	v_pk_mul_f32 v[84:85], v[84:85], v[104:105] op_sel_hi:[1,0]
	v_pk_mul_f32 v[86:87], v[86:87], v[104:105] op_sel_hi:[1,0]
	v_pk_mul_f32 v[88:89], v[88:89], v[104:105] op_sel_hi:[1,0]
	v_pk_mul_f32 v[90:91], v[90:91], v[104:105] op_sel_hi:[1,0]
	v_pk_mul_f32 v[92:93], v[92:93], v[104:105] op_sel_hi:[1,0]
	v_pk_mul_f32 v[94:95], v[94:95], v[104:105] op_sel_hi:[1,0]
	v_pk_mul_f32 v[96:97], v[96:97], v[104:105] op_sel_hi:[1,0]
	v_pk_mul_f32 v[82:83], v[82:83], v[82:83]
	v_pk_mul_f32 v[84:85], v[84:85], v[84:85]
	v_pk_mul_f32 v[86:87], v[86:87], v[86:87]
	v_pk_mul_f32 v[88:89], v[88:89], v[88:89]
	v_pk_mul_f32 v[90:91], v[90:91], v[90:91]
	v_pk_mul_f32 v[92:93], v[92:93], v[92:93]
	v_pk_mul_f32 v[94:95], v[94:95], v[94:95]
	v_pk_mul_f32 v[96:97], v[96:97], v[96:97]
	v_cvt_pk_bf16_f32 v82, v82, v83
	v_cvt_pk_bf16_f32 v83, v84, v85
	v_cvt_pk_bf16_f32 v84, v86, v87
	v_cvt_pk_bf16_f32 v85, v88, v89
	v_cvt_pk_bf16_f32 v86, v90, v91
	v_cvt_pk_bf16_f32 v87, v92, v93
	v_cvt_pk_bf16_f32 v88, v94, v95
	v_cvt_pk_bf16_f32 v89, v96, v97
	global_store_dwordx2 v[100:101], v[82:83], off
	global_store_dwordx2 v[100:101], v[84:85], off offset:32
	global_store_dwordx2 v[100:101], v[86:87], off offset:64
	global_store_dwordx2 v[100:101], v[88:89], off offset:96
	v_max_f32_e32 v87, v66, v66
	v_max_f32_e32 v66, 0, v78
	v_max_f32_e32 v78, 0, v87
	v_max_f32_e32 v88, v67, v67
	v_max_f32_e32 v67, 0, v79
	v_max_f32_e32 v79, 0, v88
	v_max_f32_e32 v89, v68, v68
	v_max_f32_e32 v68, 0, v80
	v_max_f32_e32 v80, 0, v89
	v_max_f32_e32 v82, v70, v70
	v_max_f32_e32 v83, v71, v71
	v_max_f32_e32 v84, v72, v72
	v_max_f32_e32 v85, v73, v73
	v_max_f32_e32 v90, v69, v69
	v_max_f32_e32 v69, 0, v81
	v_max_f32_e32 v70, 0, v74
	v_max_f32_e32 v71, 0, v75
	v_max_f32_e32 v72, 0, v76
	v_max_f32_e32 v73, 0, v77
	v_max_f32_e32 v74, 0, v82
	v_max_f32_e32 v75, 0, v83
	v_max_f32_e32 v76, 0, v84
	v_max_f32_e32 v77, 0, v85
	v_max_f32_e32 v81, 0, v90
	v_lshlrev_b64 v[84:85], 13, v[98:99]
	v_lshl_add_u64 v[84:85], s[6:7], 0, v[84:85]
	v_or_b32_e32 v82, 64, v106
	v_mov_b32_e32 v83, v107
	v_lshl_add_u64 v[84:85], v[84:85], 0, v[108:109]
	v_fmamk_f32 v86, v179, 0x3a800000, v137
	v_mul_f32_e32 v87, 0x4b800000, v86
	v_cmp_gt_f32_e32 vcc, s43, v86
	s_nop 1
	v_cndmask_b32_e32 v86, v86, v87, vcc
	v_rsq_f32_e32 v88, v86
	v_lshl_add_u64 v[86:87], v[82:83], 2, s[8:9]
	v_mul_f32_e32 v89, 0x45800000, v88
	v_cndmask_b32_e32 v88, v88, v89, vcc
	v_pk_mul_f32 v[66:67], v[66:67], v[88:89] op_sel_hi:[1,0]
	v_pk_mul_f32 v[68:69], v[68:69], v[88:89] op_sel_hi:[1,0]
	v_pk_mul_f32 v[70:71], v[70:71], v[88:89] op_sel_hi:[1,0]
	v_pk_mul_f32 v[72:73], v[72:73], v[88:89] op_sel_hi:[1,0]
	v_pk_mul_f32 v[74:75], v[74:75], v[88:89] op_sel_hi:[1,0]
	v_pk_mul_f32 v[76:77], v[76:77], v[88:89] op_sel_hi:[1,0]
	v_pk_mul_f32 v[78:79], v[78:79], v[88:89] op_sel_hi:[1,0]
	v_pk_mul_f32 v[80:81], v[80:81], v[88:89] op_sel_hi:[1,0]
	v_pk_mul_f32 v[66:67], v[66:67], v[66:67]
	v_pk_mul_f32 v[68:69], v[68:69], v[68:69]
	v_pk_mul_f32 v[70:71], v[70:71], v[70:71]
	v_pk_mul_f32 v[72:73], v[72:73], v[72:73]
	v_pk_mul_f32 v[74:75], v[74:75], v[74:75]
	v_pk_mul_f32 v[76:77], v[76:77], v[76:77]
	v_pk_mul_f32 v[78:79], v[78:79], v[78:79]
	v_pk_mul_f32 v[80:81], v[80:81], v[80:81]
	v_cvt_pk_bf16_f32 v66, v66, v67
	v_cvt_pk_bf16_f32 v67, v68, v69
	v_cvt_pk_bf16_f32 v68, v70, v71
	v_cvt_pk_bf16_f32 v69, v72, v73
	v_cvt_pk_bf16_f32 v70, v74, v75
	v_cvt_pk_bf16_f32 v71, v76, v77
	v_cvt_pk_bf16_f32 v72, v78, v79
	v_cvt_pk_bf16_f32 v73, v80, v81
	global_store_dwordx2 v[84:85], v[66:67], off
	global_store_dwordx2 v[84:85], v[68:69], off offset:32
	global_store_dwordx2 v[84:85], v[70:71], off offset:64
	global_store_dwordx2 v[84:85], v[72:73], off offset:96
	v_max_f32_e32 v71, v50, v50
	v_max_f32_e32 v50, 0, v62
	v_max_f32_e32 v62, 0, v71
	v_max_f32_e32 v72, v51, v51
	v_max_f32_e32 v51, 0, v63
	v_max_f32_e32 v63, 0, v72
	v_max_f32_e32 v73, v52, v52
	v_max_f32_e32 v52, 0, v64
	v_max_f32_e32 v64, 0, v73
	v_max_f32_e32 v66, v54, v54
	v_max_f32_e32 v67, v55, v55
	v_max_f32_e32 v68, v56, v56
	v_max_f32_e32 v69, v57, v57
	v_max_f32_e32 v74, v53, v53
	v_max_f32_e32 v53, 0, v65
	v_max_f32_e32 v54, 0, v58
	v_max_f32_e32 v55, 0, v59
	v_max_f32_e32 v56, 0, v60
	v_max_f32_e32 v57, 0, v61
	v_max_f32_e32 v58, 0, v66
	v_max_f32_e32 v59, 0, v67
	v_max_f32_e32 v60, 0, v68
	v_max_f32_e32 v61, 0, v69
	v_max_f32_e32 v65, 0, v74
	v_lshlrev_b64 v[68:69], 13, v[82:83]
	v_lshl_add_u64 v[68:69], s[6:7], 0, v[68:69]
	v_or_b32_e32 v66, 0x50, v106
	v_mov_b32_e32 v67, v107
	v_lshl_add_u64 v[68:69], v[68:69], 0, v[108:109]
	v_fmamk_f32 v70, v180, 0x3a800000, v137
	v_mul_f32_e32 v71, 0x4b800000, v70
	v_cmp_gt_f32_e32 vcc, s43, v70
	s_nop 1
	v_cndmask_b32_e32 v70, v70, v71, vcc
	v_rsq_f32_e32 v72, v70
	v_lshl_add_u64 v[70:71], v[66:67], 2, s[8:9]
	v_mul_f32_e32 v73, 0x45800000, v72
	v_cndmask_b32_e32 v72, v72, v73, vcc
	v_pk_mul_f32 v[50:51], v[50:51], v[72:73] op_sel_hi:[1,0]
	v_pk_mul_f32 v[52:53], v[52:53], v[72:73] op_sel_hi:[1,0]
	v_pk_mul_f32 v[54:55], v[54:55], v[72:73] op_sel_hi:[1,0]
	v_pk_mul_f32 v[56:57], v[56:57], v[72:73] op_sel_hi:[1,0]
	v_pk_mul_f32 v[58:59], v[58:59], v[72:73] op_sel_hi:[1,0]
	v_pk_mul_f32 v[60:61], v[60:61], v[72:73] op_sel_hi:[1,0]
	v_pk_mul_f32 v[62:63], v[62:63], v[72:73] op_sel_hi:[1,0]
	v_pk_mul_f32 v[64:65], v[64:65], v[72:73] op_sel_hi:[1,0]
	v_pk_mul_f32 v[50:51], v[50:51], v[50:51]
	v_pk_mul_f32 v[52:53], v[52:53], v[52:53]
	v_pk_mul_f32 v[54:55], v[54:55], v[54:55]
	v_pk_mul_f32 v[56:57], v[56:57], v[56:57]
	v_pk_mul_f32 v[58:59], v[58:59], v[58:59]
	v_pk_mul_f32 v[60:61], v[60:61], v[60:61]
	v_pk_mul_f32 v[62:63], v[62:63], v[62:63]
	v_pk_mul_f32 v[64:65], v[64:65], v[64:65]
	v_cvt_pk_bf16_f32 v50, v50, v51
	v_cvt_pk_bf16_f32 v51, v52, v53
	v_cvt_pk_bf16_f32 v52, v54, v55
	v_cvt_pk_bf16_f32 v53, v56, v57
	v_cvt_pk_bf16_f32 v54, v58, v59
	v_cvt_pk_bf16_f32 v55, v60, v61
	v_cvt_pk_bf16_f32 v56, v62, v63
	v_cvt_pk_bf16_f32 v57, v64, v65
	global_store_dwordx2 v[68:69], v[50:51], off
	global_store_dwordx2 v[68:69], v[52:53], off offset:32
	global_store_dwordx2 v[68:69], v[54:55], off offset:64
	global_store_dwordx2 v[68:69], v[56:57], off offset:96
	v_max_f32_e32 v55, v34, v34
	v_max_f32_e32 v34, 0, v46
	v_max_f32_e32 v46, 0, v55
	v_max_f32_e32 v56, v35, v35
	v_max_f32_e32 v35, 0, v47
	v_max_f32_e32 v47, 0, v56
	v_max_f32_e32 v57, v36, v36
	v_max_f32_e32 v36, 0, v48
	v_max_f32_e32 v48, 0, v57
	v_max_f32_e32 v50, v38, v38
	v_max_f32_e32 v51, v39, v39
	v_max_f32_e32 v52, v40, v40
	v_max_f32_e32 v53, v41, v41
	v_max_f32_e32 v58, v37, v37
	v_max_f32_e32 v37, 0, v49
	v_max_f32_e32 v38, 0, v42
	v_max_f32_e32 v39, 0, v43
	v_max_f32_e32 v40, 0, v44
	v_max_f32_e32 v41, 0, v45
	v_max_f32_e32 v42, 0, v50
	v_max_f32_e32 v43, 0, v51
	v_max_f32_e32 v44, 0, v52
	v_max_f32_e32 v45, 0, v53
	v_max_f32_e32 v49, 0, v58
	v_lshlrev_b64 v[52:53], 13, v[66:67]
	v_lshl_add_u64 v[52:53], s[6:7], 0, v[52:53]
	v_or_b32_e32 v50, 0x60, v106
	v_mov_b32_e32 v51, v107
	v_lshl_add_u64 v[52:53], v[52:53], 0, v[108:109]
	v_or_b32_e32 v106, 0x70, v106
	v_fmamk_f32 v54, v181, 0x3a800000, v137
	v_mul_f32_e32 v55, 0x4b800000, v54
	v_cmp_gt_f32_e32 vcc, s43, v54
	s_nop 1
	v_cndmask_b32_e32 v54, v54, v55, vcc
	v_rsq_f32_e32 v56, v54
	v_lshl_add_u64 v[54:55], v[50:51], 2, s[8:9]
	v_mul_f32_e32 v57, 0x45800000, v56
	v_cndmask_b32_e32 v56, v56, v57, vcc
	v_pk_mul_f32 v[34:35], v[34:35], v[56:57] op_sel_hi:[1,0]
	v_pk_mul_f32 v[36:37], v[36:37], v[56:57] op_sel_hi:[1,0]
	v_pk_mul_f32 v[38:39], v[38:39], v[56:57] op_sel_hi:[1,0]
	v_pk_mul_f32 v[40:41], v[40:41], v[56:57] op_sel_hi:[1,0]
	v_pk_mul_f32 v[42:43], v[42:43], v[56:57] op_sel_hi:[1,0]
	v_pk_mul_f32 v[44:45], v[44:45], v[56:57] op_sel_hi:[1,0]
	v_pk_mul_f32 v[46:47], v[46:47], v[56:57] op_sel_hi:[1,0]
	v_pk_mul_f32 v[48:49], v[48:49], v[56:57] op_sel_hi:[1,0]
	v_pk_mul_f32 v[34:35], v[34:35], v[34:35]
	v_pk_mul_f32 v[36:37], v[36:37], v[36:37]
	v_pk_mul_f32 v[38:39], v[38:39], v[38:39]
	v_pk_mul_f32 v[40:41], v[40:41], v[40:41]
	v_pk_mul_f32 v[42:43], v[42:43], v[42:43]
	v_pk_mul_f32 v[44:45], v[44:45], v[44:45]
	v_pk_mul_f32 v[46:47], v[46:47], v[46:47]
	v_pk_mul_f32 v[48:49], v[48:49], v[48:49]
	v_cvt_pk_bf16_f32 v34, v34, v35
	v_cvt_pk_bf16_f32 v35, v36, v37
	v_cvt_pk_bf16_f32 v36, v38, v39
	v_cvt_pk_bf16_f32 v37, v40, v41
	v_cvt_pk_bf16_f32 v38, v42, v43
	v_cvt_pk_bf16_f32 v39, v44, v45
	v_cvt_pk_bf16_f32 v40, v46, v47
	v_cvt_pk_bf16_f32 v41, v48, v49
	global_store_dwordx2 v[52:53], v[34:35], off
	global_store_dwordx2 v[52:53], v[36:37], off offset:32
	global_store_dwordx2 v[52:53], v[38:39], off offset:64
	global_store_dwordx2 v[52:53], v[40:41], off offset:96
	v_max_f32_e32 v37, v24, v24
	v_max_f32_e32 v24, 0, v28
	v_max_f32_e32 v28, 0, v37
	v_max_f32_e32 v38, v25, v25
	v_max_f32_e32 v25, 0, v29
	v_max_f32_e32 v29, 0, v38
	v_max_f32_e32 v39, v18, v18
	v_max_f32_e32 v18, 0, v30
	v_max_f32_e32 v30, 0, v39
	v_max_f32_e32 v34, v22, v22
	v_max_f32_e32 v35, v23, v23
	v_max_f32_e32 v40, v19, v19
	v_max_f32_e32 v41, v20, v20
	v_max_f32_e32 v42, v21, v21
	v_max_f32_e32 v19, 0, v31
	v_max_f32_e32 v20, 0, v32
	v_max_f32_e32 v21, 0, v33
	v_max_f32_e32 v22, 0, v26
	v_max_f32_e32 v23, 0, v27
	v_max_f32_e32 v26, 0, v34
	v_max_f32_e32 v27, 0, v35
	v_max_f32_e32 v31, 0, v40
	v_max_f32_e32 v32, 0, v41
	v_max_f32_e32 v33, 0, v42
	v_lshlrev_b64 v[34:35], 13, v[50:51]
	v_lshl_add_u64 v[34:35], s[6:7], 0, v[34:35]
	v_lshl_add_u64 v[34:35], v[34:35], 0, v[108:109]
	v_fmamk_f32 v36, v182, 0x3a800000, v137
	v_mul_f32_e32 v37, 0x4b800000, v36
	v_cmp_gt_f32_e32 vcc, s43, v36
	s_nop 1
	v_cndmask_b32_e32 v36, v36, v37, vcc
	v_rsq_f32_e32 v38, v36
	v_lshl_add_u64 v[36:37], v[106:107], 2, s[8:9]
	v_mul_f32_e32 v39, 0x45800000, v38
	v_cndmask_b32_e32 v38, v38, v39, vcc
	v_pk_mul_f32 v[18:19], v[18:19], v[38:39] op_sel_hi:[1,0]
	v_pk_mul_f32 v[20:21], v[20:21], v[38:39] op_sel_hi:[1,0]
	v_pk_mul_f32 v[22:23], v[22:23], v[38:39] op_sel_hi:[1,0]
	v_pk_mul_f32 v[24:25], v[24:25], v[38:39] op_sel_hi:[1,0]
	v_pk_mul_f32 v[26:27], v[26:27], v[38:39] op_sel_hi:[1,0]
	v_pk_mul_f32 v[28:29], v[28:29], v[38:39] op_sel_hi:[1,0]
	v_pk_mul_f32 v[30:31], v[30:31], v[38:39] op_sel_hi:[1,0]
	v_pk_mul_f32 v[32:33], v[32:33], v[38:39] op_sel_hi:[1,0]
	v_pk_mul_f32 v[18:19], v[18:19], v[18:19]
	v_pk_mul_f32 v[20:21], v[20:21], v[20:21]
	v_pk_mul_f32 v[22:23], v[22:23], v[22:23]
	v_pk_mul_f32 v[24:25], v[24:25], v[24:25]
	v_pk_mul_f32 v[26:27], v[26:27], v[26:27]
	v_pk_mul_f32 v[28:29], v[28:29], v[28:29]
	v_pk_mul_f32 v[30:31], v[30:31], v[30:31]
	v_pk_mul_f32 v[32:33], v[32:33], v[32:33]
	v_cvt_pk_bf16_f32 v18, v18, v19
	v_cvt_pk_bf16_f32 v19, v20, v21
	v_cvt_pk_bf16_f32 v20, v22, v23
	v_cvt_pk_bf16_f32 v21, v24, v25
	v_cvt_pk_bf16_f32 v22, v26, v27
	v_cvt_pk_bf16_f32 v23, v28, v29
	v_cvt_pk_bf16_f32 v24, v30, v31
	v_cvt_pk_bf16_f32 v25, v32, v33
	global_store_dwordx2 v[34:35], v[18:19], off
	global_store_dwordx2 v[34:35], v[20:21], off offset:32
	global_store_dwordx2 v[34:35], v[22:23], off offset:64
	global_store_dwordx2 v[34:35], v[24:25], off offset:96
	v_max_f32_e32 v19, v6, v6
	v_max_f32_e32 v6, 0, v10
	v_max_f32_e32 v10, 0, v19
	v_max_f32_e32 v20, v7, v7
	v_max_f32_e32 v7, 0, v11
	v_max_f32_e32 v11, 0, v20
	v_max_f32_e32 v21, v8, v8
	v_max_f32_e32 v8, 0, v12
	v_max_f32_e32 v12, 0, v21
	v_max_f32_e32 v22, v9, v9
	v_max_f32_e32 v23, v2, v2
	v_max_f32_e32 v24, v3, v3
	v_max_f32_e32 v25, v4, v4
	v_max_f32_e32 v26, v5, v5
	v_max_f32_e32 v2, 0, v14
	v_max_f32_e32 v3, 0, v15
	v_max_f32_e32 v4, 0, v16
	v_max_f32_e32 v5, 0, v17
	v_max_f32_e32 v9, 0, v13
	v_max_f32_e32 v13, 0, v22
	v_max_f32_e32 v14, 0, v23
	v_max_f32_e32 v15, 0, v24
	v_max_f32_e32 v16, 0, v25
	v_max_f32_e32 v17, 0, v26
	v_fmamk_f32 v18, v183, 0x3a800000, v137
	v_mul_f32_e32 v19, 0x4b800000, v18
	v_cmp_gt_f32_e32 vcc, s43, v18
	s_nop 1
	v_cndmask_b32_e32 v18, v18, v19, vcc
	v_rsq_f32_e32 v20, v18
	v_lshlrev_b64 v[18:19], 13, v[106:107]
	v_lshl_add_u64 v[18:19], s[6:7], 0, v[18:19]
	v_lshl_add_u64 v[18:19], v[18:19], 0, v[108:109]
	v_mul_f32_e32 v21, 0x45800000, v20
	v_cndmask_b32_e32 v20, v20, v21, vcc
	v_pk_mul_f32 v[2:3], v[2:3], v[20:21] op_sel_hi:[1,0]
	v_pk_mul_f32 v[4:5], v[4:5], v[20:21] op_sel_hi:[1,0]
	v_pk_mul_f32 v[6:7], v[6:7], v[20:21] op_sel_hi:[1,0]
	v_pk_mul_f32 v[8:9], v[8:9], v[20:21] op_sel_hi:[1,0]
	v_pk_mul_f32 v[10:11], v[10:11], v[20:21] op_sel_hi:[1,0]
	v_pk_mul_f32 v[12:13], v[12:13], v[20:21] op_sel_hi:[1,0]
	v_pk_mul_f32 v[14:15], v[14:15], v[20:21] op_sel_hi:[1,0]
	v_pk_mul_f32 v[16:17], v[16:17], v[20:21] op_sel_hi:[1,0]
	v_pk_mul_f32 v[2:3], v[2:3], v[2:3]
	v_pk_mul_f32 v[4:5], v[4:5], v[4:5]
	v_pk_mul_f32 v[6:7], v[6:7], v[6:7]
	v_pk_mul_f32 v[8:9], v[8:9], v[8:9]
	v_pk_mul_f32 v[10:11], v[10:11], v[10:11]
	v_pk_mul_f32 v[12:13], v[12:13], v[12:13]
	v_pk_mul_f32 v[14:15], v[14:15], v[14:15]
	v_pk_mul_f32 v[16:17], v[16:17], v[16:17]
	v_cvt_pk_bf16_f32 v2, v2, v3
	v_cvt_pk_bf16_f32 v3, v4, v5
	v_cvt_pk_bf16_f32 v4, v6, v7
	v_cvt_pk_bf16_f32 v5, v8, v9
	v_cvt_pk_bf16_f32 v6, v10, v11
	v_cvt_pk_bf16_f32 v7, v12, v13
	v_cvt_pk_bf16_f32 v8, v14, v15
	v_cvt_pk_bf16_f32 v9, v16, v17
	global_store_dwordx2 v[18:19], v[2:3], off
	global_store_dwordx2 v[18:19], v[4:5], off offset:32
	global_store_dwordx2 v[18:19], v[6:7], off offset:64
	global_store_dwordx2 v[18:19], v[8:9], off offset:96
	s_cbranch_scc0 .LBB0_563
